# v34 + own GEMM2 tile's Y counters sampled at every pop look-ahead point; GEMM2 start poll skipped when the sample already shows the 10 non-MLA units
# baseline (speedup 1.0000x reference)
.LBB0_151:
	v_readlane_b32 s0, v252, 0
	s_mov_b32 s78, s0
	v_readlane_b32 s0, v254, 5
	s_ashr_i32 s2, s0, 2
	s_and_b32 s3, s0, 3
	s_lshl_b32 s0, s2, 6
	s_ashr_i32 s1, s0, 31
	v_writelane_b32 v254, s0, 8
	s_lshl_b32 s79, s2, 5
	s_lshl_b32 s4, s2, 9
	v_writelane_b32 v254, s1, 9
	s_mov_b32 s0, s2
	v_writelane_b32 v254, s0, 10
	s_mov_b64 s[10:11], -1
	s_mov_b64 s[12:13], 0
	v_writelane_b32 v254, s1, 11
	s_lshl_b32 s0, s2, 4
	v_writelane_b32 v254, s0, 12
	v_writelane_b32 v254, s73, 13
	v_writelane_b32 v254, s80, 14
	s_cmp_lt_i32 s3, 2
	s_mov_b64 s[8:9], 0
	v_writelane_b32 v254, s81, 15
	s_cbranch_scc1 .LBB0_359
	s_cmp_eq_u32 s3, 2
	s_mov_b64 s[8:9], -1
	s_cbranch_scc0 .LBB0_358
	v_writelane_b32 v254, s3, 16
	v_cmp_eq_u32_e64 s[42:43], 0, v218
	v_readlane_b32 s0, v254, 8
	v_readlane_b32 s1, v254, 9
	s_lshl_b64 s[2:3], s[0:1], 2
	v_readlane_b32 s0, v252, 13
	s_add_u32 s2, s0, s2
	v_readlane_b32 s0, v252, 14
	s_addc_u32 s3, s0, s3
	v_writelane_b32 v254, s2, 17
	s_nop 1
	v_writelane_b32 v254, s3, 18
	s_nop 0
	v_readlane_b32 s0, v254, 10
	v_readlane_b32 s1, v254, 11
	s_lshl_b32 s0, s0, 3
	s_ashr_i32 s1, s0, 31
	v_writelane_b32 v254, s0, 19
	s_nop 1
	v_writelane_b32 v254, s1, 20
	s_add_u32 s0, s88, 0x4800000
	v_writelane_b32 v254, s0, 21
	s_addc_u32 s0, s89, 0
	v_writelane_b32 v254, s0, 23
	s_add_u32 s0, s88, 0x4e00000
	v_writelane_b32 v254, s0, 24
	s_addc_u32 s0, s89, 0
	v_writelane_b32 v254, s0, 25
	s_add_u32 s0, s88, 0x5000000
	v_writelane_b32 v254, s0, 26
	s_addc_u32 s0, s89, 0
	v_writelane_b32 v254, s0, 27
	s_add_u32 s0, s88, 0x6900000
	v_writelane_b32 v254, s0, 28
	s_addc_u32 s0, s89, 0
	v_writelane_b32 v254, s0, 30
	s_add_u32 s0, s88, 0x8200000
	v_writelane_b32 v254, s0, 31
	s_addc_u32 s0, s89, 0
	v_writelane_b32 v254, s0, 33
	s_add_u32 s0, s88, 0x8e00000
	v_writelane_b32 v254, s0, 34
	s_addc_u32 s0, s89, 0
	v_writelane_b32 v254, s0, 36
	s_add_u32 s0, s88, 0x5800000
	v_writelane_b32 v254, s0, 37
	s_addc_u32 s0, s89, 0
	v_writelane_b32 v254, s0, 39
	s_add_u32 s0, s88, 0xa00000
	v_writelane_b32 v254, s0, 41
	s_addc_u32 s0, s89, 0
	v_writelane_b32 v254, s0, 43
	s_add_u32 s0, s88, 0x400000
	v_writelane_b32 v254, s0, 44
	s_addc_u32 s0, s89, 0
	v_writelane_b32 v254, s0, 46
	s_add_u32 s0, s88, 0x600000
	v_writelane_b32 v254, s0, 48
	s_addc_u32 s0, s89, 0
	v_writelane_b32 v254, s0, 50
	s_add_u32 s0, s88, 0x3c00000
	v_writelane_b32 v254, s0, 52
	s_addc_u32 s0, s89, 0
	v_writelane_b32 v254, s0, 53
	s_add_u32 s0, s88, 0x4000000
	v_writelane_b32 v254, s0, 54
	s_addc_u32 s0, s89, 0
	v_writelane_b32 v254, s0, 56
	s_add_u32 s0, s88, 0x4400000
	v_writelane_b32 v254, s0, 57
	s_addc_u32 s0, s89, 0
	s_cmp_eq_u32 s73, 0
	v_writelane_b32 v254, s0, 58
	s_cselect_b64 s[12:13], -1, 0
	s_add_u32 s0, s88, 0x8000
	v_writelane_b32 v254, s0, 59
	s_addc_u32 s0, s89, 0
	s_add_u32 s14, s88, 0x4200
	v_writelane_b32 v254, s0, 60
	s_addc_u32 s15, s89, 0
	s_and_b32 s0, s73, 3
	s_ashr_i32 s2, s73, 2
	s_lshl_b32 s1, s2, 5
	s_lshl_b32 s2, s2, 12
	s_lshl_b32 s3, s0, 10
	s_or_b32 s80, s2, s3
	s_lshl_b32 s51, s73, 5
	s_lshl_b32 s5, s0, 12
	s_addk_i32 s80, 0x3000
	s_lshl_b32 s16, s73, 10
	s_lshl_b32 s10, s73, 3
	s_and_b32 s6, s51, 32
	s_add_i32 s7, s5, s1
	s_add_i32 s17, s16, 0
	s_add_i32 s38, s80, 0
	s_bfe_u32 s2, s73, 0x10001
	s_cmp_eq_u32 s2, 0
	s_cselect_b64 s[8:9], -1, 0
	v_writelane_b32 v254, s8, 61
	s_add_u32 s5, s88, 0xa200
	s_mov_b32 s81, s1
	v_writelane_b32 v254, s9, 62
	v_writelane_b32 v254, s5, 63
	s_addc_u32 s5, s89, 0
	s_cmp_lt_i32 s73, 4
	v_writelane_b32 v255, s5, 0
	s_cselect_b64 s[8:9], -1, 0
	v_writelane_b32 v255, s8, 2
	s_lshl_b32 s2, s2, 16
	v_readlane_b32 s5, v252, 15
	v_writelane_b32 v255, s9, 3
	s_add_u32 s2, s5, s2
	v_readlane_b32 s5, v252, 16
	s_addc_u32 s5, s5, 0
	v_writelane_b32 v255, s6, 4
	s_lshl_b32 s6, s6, 8
	s_add_u32 s2, s2, s6
	v_writelane_b32 v255, s2, 6
	s_addc_u32 s2, s5, 0
	v_writelane_b32 v255, s2, 7
	s_add_u32 s2, s88, 0x300000
	v_writelane_b32 v255, s2, 8
	s_addc_u32 s2, s89, 0
	s_add_u32 s39, s88, 0x1800
	s_addc_u32 s8, s89, 0
	v_writelane_b32 v255, s2, 9
	s_add_u32 s2, s88, 0x9000
	v_writelane_b32 v255, s2, 10
	s_addc_u32 s2, s89, 0
	v_writelane_b32 v255, s2, 11
	s_lshl_b32 s2, s73, 9
	s_add_i32 s2, s2, 0
	s_add_i32 s2, s2, 0x21800
	v_writelane_b32 v255, s2, 12
	s_add_u32 s18, s88, 0x5900000
	s_mul_i32 s2, s73, 0x2200
	s_addc_u32 s19, s89, 0
	s_add_i32 s9, s2, 0
	s_add_u32 s26, s88, 0x7200000
	s_addc_u32 s27, s89, 0
	s_lshl_b32 s2, s0, 11
	v_writelane_b32 v255, s7, 13
	s_sub_i32 s5, s7, s2
	v_writelane_b32 v255, s5, 14
	s_lshl_b32 s5, s73, 7
	s_add_i32 s6, s5, 0
	s_add_i32 s6, s6, 0x22800
	s_add_u32 s5, s88, 0x9800
	v_writelane_b32 v255, s5, 15
	s_addc_u32 s5, s89, 0
	v_writelane_b32 v255, s5, 16
	s_add_u32 s5, s88, 0x8800
	v_writelane_b32 v255, s5, 17
	s_addc_u32 s5, s89, 0
	v_writelane_b32 v255, s5, 18
	s_lshl_b32 s5, s0, 4
	s_add_i32 s3, s3, 0
	v_writelane_b32 v255, s5, 19
	s_add_i32 s7, s3, 0x2000
	v_writelane_b32 v255, s3, 20
	s_add_u32 s3, s88, 0x4410000
	v_writelane_b32 v255, s3, 22
	s_addc_u32 s3, s89, 0
	v_writelane_b32 v255, s3, 23
	s_add_u32 s3, s88, 0x4010000
	v_writelane_b32 v255, s3, 24
	s_addc_u32 s3, s89, 0
	v_writelane_b32 v255, s3, 25
	s_lshl_b32 s3, s73, 11
	v_writelane_b32 v255, s3, 26
	s_add_i32 s2, s2, s1
	v_writelane_b32 v255, s2, 27
	s_lshl_b32 s2, s0, 9
	s_mulk_i32 s0, 0x3000
	v_writelane_b32 v255, s2, 29
	s_add_i32 s0, s0, s1
	v_writelane_b32 v255, s0, 30
	v_and_b32_e32 v174, 31, v205
	v_add_u32_e32 v174, s79, v174
	v_lshlrev_b32_e32 v174, 4, v174
	v_lshrrev_b32_e32 v175, 5, v205
	v_lshl_add_u32 v174, v175, 12, v174
	v_mov_b32_e32 v175, 0
	v_readlane_b32 s100, v254, 59
	v_readlane_b32 s101, v254, 60
	s_nop 1
	v_lshl_add_u64 v[174:175], s[100:101], 0, v[174:175]
	v_readlane_b32 s100, v254, 17
	v_readlane_b32 s101, v254, 18
	s_nop 3
	v_mov_b32_e32 v182, s100
	v_mov_b32_e32 v183, s101
	s_and_b32 s100, s78, 31
	s_add_i32 s100, s100, s79
	s_lshl_b32 s100, s100, 4
	s_add_u32 s100, s39, s100
	s_addc_u32 s101, s8, 0
	v_mov_b32_e32 v176, s100
	v_mov_b32_e32 v177, s101
	s_mov_b64 s[100:101], exec
	s_mov_b64 exec, s[12:13]
	global_load_dword v184, v[174:175], off sc1
	global_load_dword v173, v[176:177], off offset:4 sc1
	global_load_dword v189, v[176:177], off sc1
	s_mov_b64 exec, s[42:43]
	global_atomic_add v221, v[182:183], v181, off sc0
	s_mov_b64 exec, s[100:101]
	s_branch .LBB0_156

.LBB0_203:
	v_add_u32_e32 v56, 0, v112
	s_waitcnt vmcnt(0)
	s_mov_b64 s[100:101], exec
	s_mov_b64 exec, s[12:13]
	global_load_dword v184, v[174:175], off sc1
	global_load_dword v173, v[176:177], off offset:4 sc1
	global_load_dword v189, v[176:177], off sc1
	s_mov_b64 exec, s[42:43]
	global_atomic_add v221, v[182:183], v181, off sc0
	s_mov_b64 exec, s[100:101]
	s_barrier
	v_add_u32_e32 v36, v56, v113
	ds_read_b128 v[32:35], v36 offset:4096
	ds_read_b128 v[48:51], v36
	v_add_u32_e32 v57, v56, v114
	ds_read_b128 v[52:55], v57 offset:4096
	ds_read_b128 v[94:97], v57
	v_add_u32_e32 v58, v56, v111
	s_waitcnt lgkmcnt(3)
	v_mfma_f32_32x32x16_bf16 v[32:47], v[32:35], v[76:79], 0
	v_add_u32_e32 v56, v56, v110
	v_readlane_b32 s0, v255, 2
	v_readlane_b32 s1, v255, 3
	s_andn2_b64 vcc, exec, s[0:1]
	ds_read_b128 v[100:103], v58
	s_waitcnt lgkmcnt(2)
	v_mfma_f32_32x32x16_bf16 v[32:47], v[52:55], v[72:75], v[32:47]
	ds_read_b128 v[52:55], v58 offset:4096
	s_waitcnt lgkmcnt(0)
	v_mfma_f32_32x32x16_bf16 v[32:47], v[52:55], v[68:71], v[32:47]
	ds_read_b128 v[52:55], v56 offset:4096
	ds_read_b128 v[110:113], v56
	s_waitcnt lgkmcnt(1)
	v_mfma_f32_32x32x16_bf16 v[32:47], v[52:55], v[64:67], v[32:47]
	v_add_u32_e32 v52, 0, v108
	v_add3_u32 v106, v52, v109, v106
	ds_read_b64_tr_b16 v[90:91], v106 offset:12288
	ds_read_b64_tr_b16 v[92:93], v106 offset:12800
	ds_read_b64_tr_b16 v[82:83], v106 offset:13312
	ds_read_b64_tr_b16 v[84:85], v106 offset:13824
	v_mfma_f32_32x32x16_bf16 v[48:63], v[48:51], v[76:79], 0
	v_add_u32_e32 v76, 0xc0, v107
	v_cvt_f32_i32_e32 v107, v76
	ds_read_b64_tr_b16 v[86:87], v106 offset:14336
	ds_read_b64_tr_b16 v[88:89], v106 offset:14848
	ds_read_b64_tr_b16 v[76:77], v106 offset:15360
	ds_read_b64_tr_b16 v[78:79], v106 offset:15872
	v_mfma_f32_32x32x16_bf16 v[48:63], v[94:97], v[72:75], v[48:63]
	v_add_f32_e32 v74, 0x41d00000, v107
	v_add_f32_e32 v75, 0x41d80000, v107
	v_add_f32_e32 v72, 0x42000000, v74
	v_add_f32_e32 v73, 0x42000000, v75
	v_fma_f32 v72, v72, v104, v105
	v_fma_f32 v73, v73, v104, v105
	v_exp_f32_e32 v72, v72
	v_mfma_f32_32x32x16_bf16 v[48:63], v[100:103], v[68:71], v[48:63]
	v_exp_f32_e32 v73, v73
	s_nop 0
	v_pk_mul_f32 v[68:69], v[46:47], v[72:73]
	v_fma_f32 v46, v74, v104, v105
	v_fma_f32 v47, v75, v104, v105
	s_waitcnt lgkmcnt(8)
	v_mfma_f32_32x32x16_bf16 v[48:63], v[110:113], v[64:67], v[48:63]
	v_exp_f32_e32 v46, v46
	v_exp_f32_e32 v47, v47
	v_add_f32_e32 v65, 0x41c80000, v107
	v_add_f32_e32 v67, 0x41980000, v107
	v_add_f32_e32 v74, 0x41200000, v107
	v_add_f32_e32 v75, 0x41300000, v107
	v_add_f32_e32 v72, 0x42000000, v74
	s_nop 4
	v_pk_mul_f32 v[62:63], v[62:63], v[46:47]
	v_add_f32_e32 v46, 0x41c00000, v107
	v_add_f32_e32 v47, 0x42000000, v46
	v_fma_f32 v47, v47, v104, v105
	v_exp_f32_e32 v64, v47
	v_fma_f32 v46, v46, v104, v105
	v_fma_f32 v47, v65, v104, v105
	v_exp_f32_e32 v46, v46
	v_exp_f32_e32 v47, v47
	v_add_f32_e32 v73, 0x42000000, v75
	v_fma_f32 v74, v74, v104, v105
	v_fma_f32 v75, v75, v104, v105
	v_pk_mul_f32 v[60:61], v[60:61], v[46:47]
	v_add_f32_e32 v46, 0x41900000, v107
	v_add_f32_e32 v47, 0x42000000, v46
	v_fma_f32 v47, v47, v104, v105
	v_exp_f32_e32 v66, v47
	v_fma_f32 v46, v46, v104, v105
	v_fma_f32 v47, v67, v104, v105
	v_exp_f32_e32 v46, v46
	v_exp_f32_e32 v47, v47
	v_exp_f32_e32 v74, v74
	v_exp_f32_e32 v75, v75
	v_fma_f32 v72, v72, v104, v105
	v_pk_mul_f32 v[58:59], v[58:59], v[46:47]
	v_add_f32_e32 v46, 0x41800000, v107
	v_add_f32_e32 v47, 0x42000000, v46
	v_fma_f32 v47, v47, v104, v105
	v_exp_f32_e32 v70, v47
	v_add_f32_e32 v47, 0x41880000, v107
	v_add_f32_e32 v71, 0x42000000, v47
	v_fma_f32 v46, v46, v104, v105
	v_fma_f32 v47, v47, v104, v105
	v_exp_f32_e32 v46, v46
	v_exp_f32_e32 v47, v47
	v_pk_mul_f32 v[54:55], v[54:55], v[74:75]
	v_add_f32_e32 v74, 2.0, v107
	v_fma_f32 v73, v73, v104, v105
	v_add_f32_e32 v75, 0x42000000, v74
	v_exp_f32_e32 v72, v72
	v_exp_f32_e32 v73, v73
	v_fma_f32 v96, v75, v104, v105
	v_add_f32_e32 v75, 0x40400000, v107
	v_pk_mul_f32 v[56:57], v[56:57], v[46:47]
	v_add_f32_e32 v46, 0x41000000, v107
	v_add_f32_e32 v94, 0x42000000, v75
	v_add_f32_e32 v47, 0x42000000, v46
	v_fma_f32 v97, v94, v104, v105
	v_add_f32_e32 v94, 0, v107
	v_fma_f32 v47, v47, v104, v105
	v_add_f32_e32 v95, 0x42000000, v94
	v_pk_mul_f32 v[38:39], v[38:39], v[72:73]
	v_exp_f32_e32 v72, v47
	v_add_f32_e32 v47, 0x41100000, v107
	v_fma_f32 v100, v95, v104, v105
	v_add_f32_e32 v95, 1.0, v107
	v_add_f32_e32 v65, 0x42000000, v65
	v_add_f32_e32 v67, 0x42000000, v67
	v_add_f32_e32 v73, 0x42000000, v47
	v_add_f32_e32 v101, 0x42000000, v95
	v_fma_f32 v65, v65, v104, v105
	v_fma_f32 v67, v67, v104, v105
	v_fma_f32 v71, v71, v104, v105
	v_fma_f32 v73, v73, v104, v105
	v_fma_f32 v46, v46, v104, v105
	v_fma_f32 v47, v47, v104, v105
	v_fma_f32 v74, v74, v104, v105
	v_fma_f32 v75, v75, v104, v105
	v_fma_f32 v101, v101, v104, v105
	v_fma_f32 v94, v94, v104, v105
	v_fmac_f32_e32 v105, v95, v104
	v_exp_f32_e32 v46, v46
	v_exp_f32_e32 v47, v47
	v_exp_f32_e32 v94, v94
	v_exp_f32_e32 v95, v105
	v_exp_f32_e32 v74, v74
	v_exp_f32_e32 v75, v75
	v_exp_f32_e32 v73, v73
	v_pk_mul_f32 v[52:53], v[52:53], v[46:47]
	v_exp_f32_e32 v96, v96
	v_pk_mul_f32 v[46:47], v[48:49], v[94:95]
	v_cvt_pk_bf16_f32 v49, v54, v55
	v_exp_f32_e32 v97, v97
	v_exp_f32_e32 v54, v100
	v_exp_f32_e32 v55, v101
	v_exp_f32_e32 v67, v67
	v_exp_f32_e32 v71, v71
	v_pk_mul_f32 v[50:51], v[50:51], v[74:75]
	v_cvt_pk_bf16_f32 v46, v46, v47
	v_cvt_pk_bf16_f32 v47, v50, v51
	v_cvt_pk_bf16_f32 v48, v52, v53
	v_pk_mul_f32 v[36:37], v[36:37], v[72:73]
	v_pk_mul_f32 v[34:35], v[34:35], v[96:97]
	v_pk_mul_f32 v[32:33], v[32:33], v[54:55]
	v_pk_mul_f32 v[42:43], v[42:43], v[66:67]
	v_cvt_pk_bf16_f32 v32, v32, v33
	v_cvt_pk_bf16_f32 v33, v34, v35
	v_cvt_pk_bf16_f32 v34, v36, v37
	v_pk_mul_f32 v[36:37], v[40:41], v[70:71]
	v_cvt_pk_bf16_f32 v50, v56, v57
	v_cvt_pk_bf16_f32 v36, v36, v37
	v_cvt_pk_bf16_f32 v37, v42, v43
	ds_read_b64_tr_b16 v[40:41], v106 offset:16384
	ds_read_b64_tr_b16 v[42:43], v106 offset:16896
	ds_read_b64_tr_b16 v[54:55], v106 offset:17408
	ds_read_b64_tr_b16 v[56:57], v106 offset:17920
	s_waitcnt lgkmcnt(10)
	v_mfma_f32_32x32x16_bf16 v[16:31], v[46:49], v[90:93], v[16:31]
	v_cvt_pk_bf16_f32 v51, v58, v59
	v_cvt_pk_bf16_f32 v52, v60, v61
	v_cvt_pk_bf16_f32 v53, v62, v63
	v_exp_f32_e32 v65, v65
	v_cvt_pk_bf16_f32 v35, v38, v39
	v_pk_mul_f32 v[38:39], v[44:45], v[64:65]
	s_waitcnt lgkmcnt(2)
	v_mfma_f32_32x32x16_bf16 v[0:15], v[46:49], v[40:43], v[0:15]
	ds_read_b64_tr_b16 v[40:41], v106 offset:18432
	ds_read_b64_tr_b16 v[42:43], v106 offset:18944
	ds_read_b64_tr_b16 v[44:45], v106 offset:19456
	ds_read_b64_tr_b16 v[46:47], v106 offset:19968
	v_cvt_pk_bf16_f32 v38, v38, v39
	v_cvt_pk_bf16_f32 v39, v68, v69
	v_mfma_f32_32x32x16_bf16 v[16:31], v[50:53], v[82:85], v[16:31]
	s_waitcnt lgkmcnt(4)
	v_mfma_f32_32x32x16_bf16 v[0:15], v[50:53], v[54:57], v[0:15]
	v_mfma_f32_32x32x16_bf16 v[16:31], v[32:35], v[86:89], v[16:31]
	s_waitcnt lgkmcnt(2)
	v_mfma_f32_32x32x16_bf16 v[0:15], v[32:35], v[40:43], v[0:15]
	v_mfma_f32_32x32x16_bf16 v[16:31], v[36:39], v[76:79], v[16:31]
	s_waitcnt lgkmcnt(0)
	v_mfma_f32_32x32x16_bf16 v[0:15], v[36:39], v[44:47], v[0:15]
	s_cbranch_vccnz .LBB0_205
	s_lshl_b32 s0, s2, 3
	s_or_b32 s36, s0, s3
	s_ashr_i32 s37, s36, 31
	s_lshl_b64 s[36:37], s[36:37], 14
	v_readlane_b32 s0, v255, 6
	s_add_u32 s36, s0, s36
	v_readlane_b32 s0, v255, 7
	v_lshlrev_b32_e32 v32, 2, v80
	s_addc_u32 s37, s0, s37
	v_ashrrev_i32_e32 v99, 31, v98
	v_ashrrev_i32_e32 v33, 31, v32
	v_or_b32_e32 v38, 1, v32
	v_lshl_add_u64 v[34:35], v[98:99], 2, s[36:37]
	v_lshlrev_b64 v[36:37], 8, v[32:33]
	v_ashrrev_i32_e32 v39, 31, v38
	v_lshl_add_u64 v[36:37], v[34:35], 0, v[36:37]
	v_lshlrev_b64 v[38:39], 8, v[38:39]
	global_store_dword v[36:37], v16, off
	v_lshl_add_u64 v[38:39], v[34:35], 0, v[38:39]
	v_or_b32_e32 v16, 2, v32
	global_store_dword v[38:39], v17, off
	v_ashrrev_i32_e32 v17, 31, v16
	v_or_b32_e32 v40, 3, v32
	v_lshlrev_b64 v[16:17], 8, v[16:17]
	v_ashrrev_i32_e32 v41, 31, v40
	v_lshl_add_u64 v[16:17], v[34:35], 0, v[16:17]
	v_lshlrev_b64 v[40:41], 8, v[40:41]
	global_store_dword v[16:17], v18, off
	v_lshl_add_u64 v[40:41], v[34:35], 0, v[40:41]
	v_add_u32_e32 v18, 8, v32
	global_store_dword v[40:41], v19, off
	v_ashrrev_i32_e32 v19, 31, v18
	v_add_u32_e32 v42, 9, v32
	v_lshlrev_b64 v[18:19], 8, v[18:19]
	v_ashrrev_i32_e32 v43, 31, v42
	v_lshl_add_u64 v[18:19], v[34:35], 0, v[18:19]
	v_lshlrev_b64 v[42:43], 8, v[42:43]
	global_store_dword v[18:19], v20, off
	v_lshl_add_u64 v[42:43], v[34:35], 0, v[42:43]
	v_add_u32_e32 v20, 10, v32
	global_store_dword v[42:43], v21, off
	v_ashrrev_i32_e32 v21, 31, v20
	v_add_u32_e32 v44, 11, v32
	v_lshlrev_b64 v[20:21], 8, v[20:21]
	v_ashrrev_i32_e32 v45, 31, v44
	v_lshl_add_u64 v[20:21], v[34:35], 0, v[20:21]
	v_lshlrev_b64 v[44:45], 8, v[44:45]
	global_store_dword v[20:21], v22, off
	v_lshl_add_u64 v[44:45], v[34:35], 0, v[44:45]
	v_add_u32_e32 v22, 16, v32
	global_store_dword v[44:45], v23, off
	v_ashrrev_i32_e32 v23, 31, v22
	v_add_u32_e32 v46, 17, v32
	v_lshlrev_b64 v[22:23], 8, v[22:23]
	v_ashrrev_i32_e32 v47, 31, v46
	v_lshl_add_u64 v[22:23], v[34:35], 0, v[22:23]
	v_lshlrev_b64 v[46:47], 8, v[46:47]
	global_store_dword v[22:23], v24, off
	v_lshl_add_u64 v[46:47], v[34:35], 0, v[46:47]
	v_add_u32_e32 v24, 18, v32
	global_store_dword v[46:47], v25, off
	v_ashrrev_i32_e32 v25, 31, v24
	v_add_u32_e32 v48, 19, v32
	v_lshlrev_b64 v[24:25], 8, v[24:25]
	v_ashrrev_i32_e32 v49, 31, v48
	v_lshl_add_u64 v[24:25], v[34:35], 0, v[24:25]
	v_lshlrev_b64 v[48:49], 8, v[48:49]
	global_store_dword v[24:25], v26, off
	v_lshl_add_u64 v[48:49], v[34:35], 0, v[48:49]
	v_add_u32_e32 v26, 24, v32
	global_store_dword v[48:49], v27, off
	v_ashrrev_i32_e32 v27, 31, v26
	v_add_u32_e32 v50, 25, v32
	v_lshlrev_b64 v[26:27], 8, v[26:27]
	v_ashrrev_i32_e32 v51, 31, v50
	v_lshl_add_u64 v[26:27], v[34:35], 0, v[26:27]
	v_lshlrev_b64 v[50:51], 8, v[50:51]
	global_store_dword v[26:27], v28, off
	v_lshl_add_u64 v[50:51], v[34:35], 0, v[50:51]
	v_add_u32_e32 v28, 26, v32
	v_add_u32_e32 v32, 27, v32
	global_store_dword v[50:51], v29, off
	v_ashrrev_i32_e32 v29, 31, v28
	v_ashrrev_i32_e32 v33, 31, v32
	v_lshlrev_b64 v[28:29], 8, v[28:29]
	v_lshlrev_b64 v[32:33], 8, v[32:33]
	v_lshl_add_u64 v[28:29], v[34:35], 0, v[28:29]
	v_lshl_add_u64 v[32:33], v[34:35], 0, v[32:33]
	global_store_dword v[28:29], v30, off
	global_store_dword v[32:33], v31, off
	global_store_dword v[36:37], v0, off offset:128
	global_store_dword v[38:39], v1, off offset:128
	global_store_dword v[16:17], v2, off offset:128
	global_store_dword v[40:41], v3, off offset:128
	global_store_dword v[18:19], v4, off offset:128
	global_store_dword v[42:43], v5, off offset:128
	global_store_dword v[20:21], v6, off offset:128
	global_store_dword v[44:45], v7, off offset:128
	global_store_dword v[22:23], v8, off offset:128
	global_store_dword v[46:47], v9, off offset:128
	global_store_dword v[24:25], v10, off offset:128
	global_store_dword v[48:49], v11, off offset:128
	global_store_dword v[26:27], v12, off offset:128
	global_store_dword v[50:51], v13, off offset:128
	global_store_dword v[28:29], v14, off offset:128
	global_store_dword v[32:33], v15, off offset:128

.LBB0_242:
	s_mul_i32 s37, s60, 0x5000
	s_add_i32 s37, s37, 0
	v_add_u32_e32 v36, s37, v144
	s_waitcnt vmcnt(0)
	s_mov_b64 s[100:101], exec
	s_mov_b64 exec, s[12:13]
	global_load_dword v184, v[174:175], off sc1
	global_load_dword v173, v[176:177], off offset:4 sc1
	global_load_dword v189, v[176:177], off sc1
	s_mov_b64 exec, s[42:43]
	global_atomic_add v221, v[182:183], v181, off sc0
	s_mov_b64 exec, s[100:101]
	s_barrier
	v_add_u32_e32 v32, v36, v151
	ds_read_b128 v[48:51], v32
	ds_read_b128 v[32:35], v32 offset:4096
	v_add_u32_e32 v37, v36, v145
	ds_read_b128 v[64:67], v37
	ds_read_b128 v[52:55], v37 offset:4096
	v_add_u32_e32 v37, v36, v146
	v_add_u32_e32 v36, v36, v147
	ds_read_b128 v[68:71], v37
	ds_read_b128 v[56:59], v37 offset:4096
	ds_read_b128 v[72:75], v36
	ds_read_b128 v[60:63], v36 offset:4096
	s_waitcnt lgkmcnt(6)
	v_mfma_f32_32x32x16_bf16 v[32:47], v[32:35], v[94:97], 0
	s_lshl_b32 s0, s54, 6
	v_add_u32_e32 v130, s33, v116
	s_mov_b32 s1, 0x800000
	s_mov_b32 s72, 0x40c00000
	s_mov_b64 s[66:67], 0x4000
	v_readlane_b32 s73, v254, 13
	s_waitcnt lgkmcnt(4)
	v_mfma_f32_32x32x16_bf16 v[32:47], v[52:55], v[90:93], v[32:47]
	v_add3_u32 v52, s37, v117, v143
	v_add_u32_e32 v131, v52, v142
	ds_read_b64_tr_b16 v[110:111], v131 offset:12288
	ds_read_b64_tr_b16 v[112:113], v131 offset:12800
	ds_read_b64_tr_b16 v[106:107], v131 offset:13312
	ds_read_b64_tr_b16 v[108:109], v131 offset:13824
	ds_read_b64_tr_b16 v[102:103], v131 offset:14336
	ds_read_b64_tr_b16 v[104:105], v131 offset:14848
	ds_read_b64_tr_b16 v[98:99], v131 offset:15360
	ds_read_b64_tr_b16 v[100:101], v131 offset:15872
	s_add_i32 s37, s0, 0xffffff80
	s_addk_i32 s0, 0xffbf
	s_cmp_ge_u32 s0, s33
	s_cselect_b64 s[58:59], -1, 0
	s_waitcnt lgkmcnt(10)
	v_mfma_f32_32x32x16_bf16 v[32:47], v[56:59], v[86:89], v[32:47]
	s_cmp_lt_u32 s0, s33
	s_cselect_b64 s[54:55], -1, 0
	s_cmp_gt_u32 s37, s50
	s_cselect_b64 s[62:63], -1, 0
	s_or_b64 s[54:55], s[54:55], s[62:63]
	s_mov_b64 s[62:63], -1
	s_and_b64 vcc, exec, s[54:55]
	s_waitcnt lgkmcnt(8)
	v_mfma_f32_32x32x16_bf16 v[32:47], v[60:63], v[82:85], v[32:47]
	v_mfma_f32_32x32x16_bf16 v[48:63], v[48:51], v[94:97], 0
	v_mfma_f32_32x32x16_bf16 v[48:63], v[64:67], v[90:93], v[48:63]
	v_mfma_f32_32x32x16_bf16 v[48:63], v[68:71], v[86:89], v[48:63]
	v_mfma_f32_32x32x16_bf16 v[48:63], v[72:75], v[82:85], v[48:63]
	s_cbranch_vccnz .LBB0_244
	v_add_u32_e32 v64, s37, v141
	v_sub_u32_e32 v64, v130, v64
	v_cvt_f32_i32_e32 v64, v64
	s_mov_b32 s0, 0xc2000000
	v_cmp_lt_f32_e32 vcc, 0, v64
	v_add_f32_e32 v65, -1.0, v64
	s_mov_b32 s54, -2.0
	v_cndmask_b32_e32 v66, v137, v115, vcc
	v_mul_f32_e64 v66, |v64|, v66
	v_cmp_lt_f32_e32 vcc, 0, v65
	v_exp_f32_e32 v133, v66
	s_mov_b32 s55, 0xc0400000
	v_cndmask_b32_e32 v66, v137, v115, vcc
	v_mul_f32_e64 v66, |v65|, v66
	v_exp_f32_e32 v134, v66
	v_pk_add_f32 v[66:67], v[64:65], s[0:1] op_sel_hi:[1,0]
	s_mov_b64 s[62:63], 0
	v_cmp_lt_f32_e32 vcc, 0, v66
	s_nop 1
	v_cndmask_b32_e32 v68, v137, v115, vcc
	v_cmp_lt_f32_e32 vcc, 0, v67
	v_mul_f32_e64 v68, |v66|, v68
	v_exp_f32_e32 v68, v68
	v_cndmask_b32_e32 v69, v137, v115, vcc
	v_mul_f32_e64 v69, |v67|, v69
	v_exp_f32_e32 v69, v69
	v_cmp_neq_f32_e32 vcc, 0, v67
	s_nop 1
	v_cndmask_b32_e32 v67, 2.0, v69, vcc
	v_cmp_neq_f32_e32 vcc, 0, v66
	s_nop 1
	v_cndmask_b32_e32 v66, 2.0, v68, vcc
	v_pk_mul_f32 v[116:117], v[32:33], v[66:67]
	v_pk_add_f32 v[66:67], v[64:65], s[54:55] op_sel_hi:[0,1]
	v_cmp_lt_f32_e32 vcc, 0, v66
	s_mov_b32 s54, 0xc1000000
	s_mov_b32 s55, 0xc1100000
	v_cndmask_b32_e32 v68, v137, v115, vcc
	v_mul_f32_e64 v68, |v66|, v68
	v_cmp_lt_f32_e32 vcc, 0, v67
	v_exp_f32_e32 v135, v68
	s_nop 0
	v_cndmask_b32_e32 v68, v137, v115, vcc
	v_mul_f32_e64 v68, |v67|, v68
	v_exp_f32_e32 v141, v68
	v_pk_add_f32 v[68:69], v[66:67], s[0:1] op_sel_hi:[1,0]
	s_nop 0
	v_cmp_lt_f32_e32 vcc, 0, v68
	s_nop 1
	v_cndmask_b32_e32 v70, v137, v115, vcc
	v_cmp_lt_f32_e32 vcc, 0, v69
	v_mul_f32_e64 v70, |v68|, v70
	v_exp_f32_e32 v70, v70
	v_cndmask_b32_e32 v71, v137, v115, vcc
	v_mul_f32_e64 v71, |v69|, v71
	v_exp_f32_e32 v71, v71
	v_cmp_neq_f32_e32 vcc, 0, v69
	s_nop 1
	v_cndmask_b32_e32 v69, 2.0, v71, vcc
	v_cmp_neq_f32_e32 vcc, 0, v68
	s_nop 1
	v_cndmask_b32_e32 v68, 2.0, v70, vcc
	v_pk_mul_f32 v[118:119], v[34:35], v[68:69]
	v_pk_add_f32 v[68:69], v[64:65], s[54:55] op_sel_hi:[0,1]
	v_cmp_lt_f32_e32 vcc, 0, v68
	s_mov_b32 s54, 0xc1200000
	s_mov_b32 s55, 0xc1300000
	v_cndmask_b32_e32 v70, v137, v115, vcc
	v_mul_f32_e64 v70, |v68|, v70
	v_cmp_lt_f32_e32 vcc, 0, v69
	v_exp_f32_e32 v142, v70
	s_nop 0
	v_cndmask_b32_e32 v70, v137, v115, vcc
	v_mul_f32_e64 v70, |v69|, v70
	v_exp_f32_e32 v143, v70
	v_pk_add_f32 v[70:71], v[68:69], s[0:1] op_sel_hi:[1,0]
	s_nop 0
	v_cmp_lt_f32_e32 vcc, 0, v70
	s_nop 1
	v_cndmask_b32_e32 v72, v137, v115, vcc
	v_cmp_lt_f32_e32 vcc, 0, v71
	v_mul_f32_e64 v72, |v70|, v72
	v_exp_f32_e32 v72, v72
	v_cndmask_b32_e32 v73, v137, v115, vcc
	v_mul_f32_e64 v73, |v71|, v73
	v_exp_f32_e32 v73, v73
	v_cmp_neq_f32_e32 vcc, 0, v71
	s_nop 1
	v_cndmask_b32_e32 v71, 2.0, v73, vcc
	v_cmp_neq_f32_e32 vcc, 0, v70
	s_nop 1
	v_cndmask_b32_e32 v70, 2.0, v72, vcc
	v_pk_mul_f32 v[120:121], v[36:37], v[70:71]
	v_pk_add_f32 v[70:71], v[64:65], s[54:55] op_sel_hi:[0,1]
	v_cmp_lt_f32_e32 vcc, 0, v70
	s_mov_b32 s54, 0xc1800000
	s_mov_b32 s55, 0xc1880000
	v_cndmask_b32_e32 v72, v137, v115, vcc
	v_mul_f32_e64 v72, |v70|, v72
	v_cmp_lt_f32_e32 vcc, 0, v71
	v_exp_f32_e32 v144, v72
	s_nop 0
	v_cndmask_b32_e32 v72, v137, v115, vcc
	v_mul_f32_e64 v72, |v71|, v72
	v_exp_f32_e32 v145, v72
	v_pk_add_f32 v[72:73], v[70:71], s[0:1] op_sel_hi:[1,0]
	s_nop 0
	v_cmp_lt_f32_e32 vcc, 0, v72
	s_nop 1
	v_cndmask_b32_e32 v74, v137, v115, vcc
	v_cmp_lt_f32_e32 vcc, 0, v73
	v_mul_f32_e64 v74, |v72|, v74
	v_exp_f32_e32 v74, v74
	v_cndmask_b32_e32 v75, v137, v115, vcc
	v_mul_f32_e64 v75, |v73|, v75
	v_exp_f32_e32 v75, v75
	v_cmp_neq_f32_e32 vcc, 0, v73
	s_nop 1
	v_cndmask_b32_e32 v73, 2.0, v75, vcc
	v_cmp_neq_f32_e32 vcc, 0, v72
	s_nop 1
	v_cndmask_b32_e32 v72, 2.0, v74, vcc
	v_pk_mul_f32 v[122:123], v[38:39], v[72:73]
	v_pk_add_f32 v[72:73], v[64:65], s[54:55] op_sel_hi:[0,1]
	v_cmp_lt_f32_e32 vcc, 0, v72
	s_mov_b32 s54, 0xc1900000
	s_mov_b32 s55, 0xc1980000
	v_cndmask_b32_e32 v74, v137, v115, vcc
	v_mul_f32_e64 v74, |v72|, v74
	v_cmp_lt_f32_e32 vcc, 0, v73
	v_exp_f32_e32 v146, v74
	s_nop 0
	v_cndmask_b32_e32 v74, v137, v115, vcc
	v_mul_f32_e64 v74, |v73|, v74
	v_exp_f32_e32 v147, v74
	v_pk_add_f32 v[74:75], v[72:73], s[0:1] op_sel_hi:[1,0]
	s_nop 0
	v_cmp_lt_f32_e32 vcc, 0, v74
	s_nop 1
	v_cndmask_b32_e32 v76, v137, v115, vcc
	v_cmp_lt_f32_e32 vcc, 0, v75
	v_mul_f32_e64 v76, |v74|, v76
	v_exp_f32_e32 v76, v76
	v_cndmask_b32_e32 v77, v137, v115, vcc
	v_mul_f32_e64 v77, |v75|, v77
	v_exp_f32_e32 v77, v77
	v_cmp_neq_f32_e32 vcc, 0, v75
	s_nop 1
	v_cndmask_b32_e32 v75, 2.0, v77, vcc
	v_cmp_neq_f32_e32 vcc, 0, v74
	s_nop 1
	v_cndmask_b32_e32 v74, 2.0, v76, vcc
	v_pk_mul_f32 v[124:125], v[40:41], v[74:75]
	v_pk_add_f32 v[74:75], v[64:65], s[54:55] op_sel_hi:[0,1]
	v_cmp_lt_f32_e32 vcc, 0, v74
	s_mov_b32 s54, 0xc1c00000
	s_mov_b32 s55, 0xc1c80000
	v_cndmask_b32_e32 v76, v137, v115, vcc
	v_mul_f32_e64 v76, |v74|, v76
	v_cmp_lt_f32_e32 vcc, 0, v75
	v_exp_f32_e32 v151, v76
	s_nop 0
	v_cndmask_b32_e32 v76, v137, v115, vcc
	v_mul_f32_e64 v76, |v75|, v76
	v_exp_f32_e32 v152, v76
	v_pk_add_f32 v[76:77], v[74:75], s[0:1] op_sel_hi:[1,0]
	s_nop 0
	v_cmp_lt_f32_e32 vcc, 0, v76
	s_nop 1
	v_cndmask_b32_e32 v78, v137, v115, vcc
	v_cmp_lt_f32_e32 vcc, 0, v77
	v_mul_f32_e64 v78, |v76|, v78
	v_exp_f32_e32 v78, v78
	v_cndmask_b32_e32 v79, v137, v115, vcc
	v_mul_f32_e64 v79, |v77|, v79
	v_exp_f32_e32 v79, v79
	v_cmp_neq_f32_e32 vcc, 0, v77
	s_nop 1
	v_cndmask_b32_e32 v77, 2.0, v79, vcc
	v_cmp_neq_f32_e32 vcc, 0, v76
	s_nop 1
	v_cndmask_b32_e32 v76, 2.0, v78, vcc
	v_pk_mul_f32 v[126:127], v[42:43], v[76:77]
	v_pk_add_f32 v[76:77], v[64:65], s[54:55] op_sel_hi:[0,1]
	v_cmp_lt_f32_e32 vcc, 0, v76
	s_mov_b32 s54, 0xc1d00000
	s_mov_b32 s55, 0xc1d80000
	v_cndmask_b32_e32 v78, v137, v115, vcc
	v_mul_f32_e64 v78, |v76|, v78
	v_cmp_lt_f32_e32 vcc, 0, v77
	v_exp_f32_e32 v153, v78
	s_nop 0
	v_cndmask_b32_e32 v78, v137, v115, vcc
	v_mul_f32_e64 v78, |v77|, v78
	v_exp_f32_e32 v154, v78
	v_pk_add_f32 v[78:79], v[76:77], s[0:1] op_sel_hi:[1,0]
	s_nop 0
	v_cmp_lt_f32_e32 vcc, 0, v78
	s_nop 1
	v_cndmask_b32_e32 v128, v137, v115, vcc
	v_cmp_lt_f32_e32 vcc, 0, v79
	v_mul_f32_e64 v128, |v78|, v128
	v_exp_f32_e32 v128, v128
	v_cndmask_b32_e32 v129, v137, v115, vcc
	v_mul_f32_e64 v129, |v79|, v129
	v_exp_f32_e32 v129, v129
	v_cmp_neq_f32_e32 vcc, 0, v79
	s_nop 1
	v_cndmask_b32_e32 v79, 2.0, v129, vcc
	v_cmp_neq_f32_e32 vcc, 0, v78
	s_nop 1
	v_cndmask_b32_e32 v78, 2.0, v128, vcc
	v_pk_mul_f32 v[128:129], v[44:45], v[78:79]
	v_pk_add_f32 v[78:79], v[64:65], s[54:55] op_sel_hi:[0,1]
	v_add_f32_e32 v132, 0xc2000000, v78
	v_cmp_lt_f32_e32 vcc, 0, v78
	s_nop 1
	v_cndmask_b32_e32 v155, v137, v115, vcc
	v_cmp_lt_f32_e32 vcc, 0, v132
	v_mul_f32_e64 v155, |v78|, v155
	v_exp_f32_e32 v155, v155
	v_cndmask_b32_e32 v156, v137, v115, vcc
	v_mul_f32_e64 v156, |v132|, v156
	v_exp_f32_e32 v156, v156
	v_cmp_lt_f32_e32 vcc, 0, v79
	s_nop 1
	v_cndmask_b32_e32 v157, v137, v115, vcc
	v_mul_f32_e64 v157, |v79|, v157
	v_exp_f32_e32 v157, v157
	v_cmp_neq_f32_e32 vcc, 0, v132
	s_nop 1
	v_cndmask_b32_e32 v132, 2.0, v156, vcc
	v_add_f32_e32 v156, 0xc2000000, v79
	v_cmp_lt_f32_e32 vcc, 0, v156
	v_mul_f32_e32 v132, v46, v132
	s_nop 0
	v_cndmask_b32_e32 v158, v137, v115, vcc
	v_cmp_neq_f32_e32 vcc, 0, v79
	v_mul_f32_e64 v158, |v156|, v158
	v_exp_f32_e32 v158, v158
	v_cndmask_b32_e32 v79, 2.0, v157, vcc
	v_cmp_neq_f32_e32 vcc, 0, v78
	s_nop 1
	v_cndmask_b32_e32 v78, 2.0, v155, vcc
	v_cmp_neq_f32_e32 vcc, 0, v77
	s_nop 1
	v_cndmask_b32_e32 v77, 2.0, v154, vcc
	v_cmp_neq_f32_e32 vcc, 0, v76
	s_nop 1
	v_cndmask_b32_e32 v76, 2.0, v153, vcc
	v_cmp_neq_f32_e32 vcc, 0, v75
	s_nop 1
	v_cndmask_b32_e32 v75, 2.0, v152, vcc
	v_cmp_neq_f32_e32 vcc, 0, v74
	s_nop 1
	v_cndmask_b32_e32 v74, 2.0, v151, vcc
	v_cmp_neq_f32_e32 vcc, 0, v73
	s_nop 1
	v_cndmask_b32_e32 v73, 2.0, v147, vcc
	v_cmp_neq_f32_e32 vcc, 0, v72
	s_nop 1
	v_cndmask_b32_e32 v72, 2.0, v146, vcc
	v_cmp_neq_f32_e32 vcc, 0, v71
	s_nop 1
	v_cndmask_b32_e32 v71, 2.0, v145, vcc
	v_cmp_neq_f32_e32 vcc, 0, v70
	s_nop 1
	v_cndmask_b32_e32 v70, 2.0, v144, vcc
	v_cmp_neq_f32_e32 vcc, 0, v69
	s_nop 1
	v_cndmask_b32_e32 v69, 2.0, v143, vcc
	v_cmp_neq_f32_e32 vcc, 0, v68
	s_nop 1
	v_cndmask_b32_e32 v68, 2.0, v142, vcc
	v_cmp_neq_f32_e32 vcc, 0, v67
	s_nop 1
	v_cndmask_b32_e32 v67, 2.0, v141, vcc
	v_cmp_neq_f32_e32 vcc, 0, v66
	s_nop 1
	v_cndmask_b32_e32 v66, 2.0, v135, vcc
	v_cmp_neq_f32_e32 vcc, 0, v64
	s_nop 1
	v_cndmask_b32_e32 v64, 2.0, v133, vcc
	v_cmp_neq_f32_e32 vcc, 0, v65
	s_nop 1
	v_cndmask_b32_e32 v65, 2.0, v134, vcc
	v_cmp_neq_f32_e32 vcc, 0, v156
	s_nop 1
	v_cndmask_b32_e32 v133, 2.0, v158, vcc

.LBB0_291:
	s_waitcnt vmcnt(0)
	s_mov_b64 s[100:101], exec
	s_mov_b64 exec, s[12:13]
	global_load_dword v184, v[174:175], off sc1
	global_load_dword v173, v[176:177], off offset:4 sc1
	global_load_dword v189, v[176:177], off sc1
	s_mov_b64 exec, s[42:43]
	global_atomic_add v221, v[182:183], v181, off sc0
	s_mov_b64 exec, s[100:101]
	s_mov_b64 s[44:45], 0

.LBB0_342:
	s_waitcnt vmcnt(0)
	s_mov_b64 s[100:101], exec
	s_mov_b64 exec, s[12:13]
	global_load_dword v184, v[174:175], off sc1
	global_load_dword v173, v[176:177], off offset:4 sc1
	global_load_dword v189, v[176:177], off sc1
	s_mov_b64 exec, s[42:43]
	global_atomic_add v221, v[182:183], v181, off sc0
	s_mov_b64 exec, s[100:101]
	s_mov_b64 s[28:29], 0

.LBB0_354:
	s_or_b64 exec, exec, s[28:29]
	s_andn2_b64 vcc, exec, s[12:13]
	s_cbranch_vccnz .Lmz_done
	s_ashr_i32 s100, s5, 8
	s_add_i32 s100, s100, s79
	s_lshl_b32 s100, s100, 4
	v_readlane_b32 s101, v255, 10
	s_add_u32 s100, s101, s100
	v_readlane_b32 s101, v255, 11
	s_addc_u32 s101, s101, 0
	v_mov_b32_e32 v190, s100
	v_mov_b32_e32 v191, s101
	s_movk_i32 s100, 0
.Lmz_spin:
	global_load_dword v192, v[190:191], off sc1
	s_waitcnt vmcnt(0)
	v_readfirstlane_b32 s101, v192
	s_cmp_gt_u32 s101, 3
	s_cbranch_scc1 .Lmz_done
	s_add_i32 s100, s100, 1
	s_cmp_gt_u32 s100, 0xffff
	s_cbranch_scc1 .Lmz_done
	s_sleep 1
	s_branch .Lmz_spin

.LBB0_365:
	s_and_b32 s73, s72, 31
	s_and_saveexec_b64 s[16:17], s[38:39]
	s_cbranch_execz .LBB0_392
	s_lshl_b32 s0, s73, 2
	v_readlane_b32 s18, v254, 28
	v_readlane_b32 s19, v254, 29
	s_or_b32 s18, s0, s18
	s_ashr_i32 s19, s18, 31
	s_lshl_b64 s[18:19], s[18:19], 2
	v_readlane_b32 s26, v252, 29
	v_readlane_b32 s27, v252, 30
	s_add_u32 s18, s26, s18
	s_addc_u32 s19, s27, s19
	v_mov_b32_e32 v176, s18
	v_mov_b32_e32 v177, s19
	s_cmp_lg_u32 s72, s78
	s_cbranch_scc1 .Lg2_nopre
	v_mov_b32_e32 v192, v189
	v_cmp_lt_u32_e32 vcc, 9, v173
	s_cbranch_vccnz .LBB0_379
.Lg2_nopre:
	global_load_dword v0, v81, s[18:19] offset:4 sc1
	global_load_dword v192, v81, s[18:19] sc1
	s_waitcnt vmcnt(0)
	v_cmp_lt_u32_e32 vcc, 9, v0
	s_cbranch_vccnz .LBB0_379
	s_mov_b32 s0, 1
	s_branch .LBB0_369
